# row-scale table builder of the in-proj and FFN-up GEMM phases runs one pass instead of two (workgroups have at most 4 / 8 tiles there)
# speedup vs baseline: 1.0017x; 1.0017x over previous
; #define LAS __attribute__((address_space(3)))
; __device__ __forceinline__ void build_rs_table(LAS float* rstab, const StaticOrder& S, const float* ssq) {
;     int tid = threadIdx.x; asm volatile("" : "+v"(tid));
;     Unit u;
; #pragma unroll 1
;     for (int i0 = 0; i0 < 16; i0 += 8) {
;         f32x4 pv[4][4]; bool ok[4];
; #pragma unroll
;         for (int q = 0; q < 4; ++q) { const int i = i0 + 2 * q + (tid >> 8); ok[q] = S.next(i, u);
;             const f32x4* pp = (const f32x4*)(ssq + (size_t)((ok[q] ? u.pm : 0) * BM + (tid & 255)) * 16);
; #pragma unroll
;             for (int j = 0; j < 4; ++j) pv[q][j] = pp[j]; }
; #pragma unroll
;         for (int q = 0; q < 4; ++q) { const int i = i0 + 2 * q + (tid >> 8);
;             const f32x4 a = pv[q][0], b = pv[q][1], c = pv[q][2], d = pv[q][3];
;             const float sm = ((a[0] + a[1]) + (a[2] + a[3])) + ((b[0] + b[1]) + (b[2] + b[3])) + ((c[0] + c[1]) + (c[2] + c[3])) + ((d[0] + d[1]) + (d[2] + d[3]));
;             if (ok[q]) rstab[i * 256 + (tid & 255)] = 1.0f / sqrtf(sm * (1.0f / DM) + EPS); }
;     }
;     __syncthreads();
.LBB0_126:
	s_or_b64 exec, exec, s[10:11]
	s_mov_b32 s4, 8
	s_andn2_b64 vcc, exec, s[8:9]
	s_mov_b64 s[8:9], 0
	s_branch .LBB0_159

; #define LAS __attribute__((address_space(3)))
; __device__ __forceinline__ void build_rs_table(LAS float* rstab, const StaticOrder& S, const float* ssq) {
;     int tid = threadIdx.x; asm volatile("" : "+v"(tid));
;     Unit u;
; #pragma unroll 1
;     for (int i0 = 0; i0 < 16; i0 += 8) {
;         f32x4 pv[4][4]; bool ok[4];
; #pragma unroll
;         for (int q = 0; q < 4; ++q) { const int i = i0 + 2 * q + (tid >> 8); ok[q] = S.next(i, u);
;             const f32x4* pp = (const f32x4*)(ssq + (size_t)((ok[q] ? u.pm : 0) * BM + (tid & 255)) * 16);
; #pragma unroll
;             for (int j = 0; j < 4; ++j) pv[q][j] = pp[j]; }
; #pragma unroll
;         for (int q = 0; q < 4; ++q) { const int i = i0 + 2 * q + (tid >> 8);
;             const f32x4 a = pv[q][0], b = pv[q][1], c = pv[q][2], d = pv[q][3];
;             const float sm = ((a[0] + a[1]) + (a[2] + a[3])) + ((b[0] + b[1]) + (b[2] + b[3])) + ((c[0] + c[1]) + (c[2] + c[3])) + ((d[0] + d[1]) + (d[2] + d[3]));
;             if (ok[q]) rstab[i * 256 + (tid & 255)] = 1.0f / sqrtf(sm * (1.0f / DM) + EPS); }
;     }
;     __syncthreads();
.LBB0_439:
	s_or_b64 exec, exec, s[8:9]
	s_xor_b64 s[6:7], s[6:7], -1
	s_mov_b32 s10, 8
	s_andn2_b64 vcc, exec, s[6:7]
	s_mov_b64 s[6:7], 0
	s_branch .LBB0_456
